# fox attention: forget-gate cumsum stored negated in LDS so score accumulators load directly (drops 32 v_xor per tile); on top of pipelined fragment reads + gemm saddr
# speedup vs baseline: 1.0022x; 1.0022x over previous
.LBB0_672:
	s_or_b64 exec, exec, s[56:57]
	v_cmp_gt_u32_e64 s[12:13], 32, v4
	s_nop 1
	v_cndmask_b32_e64 v4, v10, v9, s[12:13]
	v_sub_f32_e32 v4, v4, v2
	v_add_f32_e32 v5, v4, v11
	v_lshl_add_u32 v4, v0, 2, 0
	s_and_saveexec_b64 s[12:13], vcc
	s_cbranch_execz .LBB0_712
	v_add_f32_e32 v6, v6, v5
	v_mul_f32_e32 v6, 0xbfb8aa3b, v6
	v_cmp_lt_i32_e32 vcc, 47, v0
	s_nop 1
	v_cndmask_b32_e32 v6, v239, v6, vcc
	ds_write_b32 v4, v6
	s_or_b64 exec, exec, s[12:13]
	s_and_saveexec_b64 s[12:13], s[0:1]
	s_cbranch_execnz .LBB0_713

.LBB0_675:
	v_add_f32_e32 v6, v7, v5
	v_mul_f32_e32 v6, 0xbfb8aa3b, v6
	v_cmp_lt_i32_e32 vcc, 45, v0
	s_nop 1
	v_cndmask_b32_e32 v6, v239, v6, vcc
	ds_write_b32 v4, v6 offset:8
	s_or_b64 exec, exec, s[0:1]
	s_and_saveexec_b64 s[0:1], s[6:7]
	s_cbranch_execnz .LBB0_715

.LBB0_677:
	v_add_f32_e32 v2, v2, v5
	v_mul_f32_e32 v2, 0xbfb8aa3b, v2
	v_cmp_lt_i32_e32 vcc, 43, v0
	s_nop 1
	v_cndmask_b32_e32 v0, v239, v2, vcc
	ds_write_b32 v4, v0 offset:16

.LBB0_683:
	s_and_b32 s79, s18, 1
	s_cmp_gt_i32 s78, s77
	s_cbranch_scc1 .LBB0_692
	s_mul_i32 s20, s79, 0x4400
	ds_read_b128 v[80:83], v172
	ds_read_b128 v[84:87], v172 offset:16
	ds_read_b128 v[88:91], v172 offset:64
	ds_read_b128 v[92:95], v172 offset:80
	v_add_u32_e32 v0, s20, v164
	ds_read_b128 v[206:209], v0 offset:8704
	ds_read_b128 v[210:213], v0 offset:8736
	ds_read_b128 v[214:217], v0 offset:8768
	ds_read_b128 v[218:221], v0 offset:8800
	ds_read_b128 v[222:225], v0 offset:8832
	ds_read_b128 v[226:229], v0 offset:8864
	s_waitcnt lgkmcnt(6)
	s_add_i32 s20, s78, 63
	s_cmp_ge_i32 s20, s75
	s_mov_b64 s[56:57], -1
	s_waitcnt lgkmcnt(5)
	v_mfma_f32_32x32x16_bf16 v[80:95], v[206:209], v[140:143], v[80:95]
	ds_read_b128 v[206:209], v0 offset:8896
	s_waitcnt lgkmcnt(5)
	v_mfma_f32_32x32x16_bf16 v[80:95], v[210:213], v[136:139], v[80:95]
	ds_read_b128 v[210:213], v0 offset:8928
	ds_read_b128 v[96:99], v172 offset:128
	ds_read_b128 v[100:103], v172 offset:144
	ds_read_b128 v[104:107], v172 offset:192
	ds_read_b128 v[108:111], v172 offset:208
	s_waitcnt lgkmcnt(9)
	v_mfma_f32_32x32x16_bf16 v[80:95], v[214:217], v[132:135], v[80:95]
	ds_read_b128 v[214:217], v0 offset:17408
	s_waitcnt lgkmcnt(9)
	v_mfma_f32_32x32x16_bf16 v[80:95], v[218:221], v[128:131], v[80:95]
	ds_read_b128 v[218:221], v0 offset:17440
	s_waitcnt lgkmcnt(9)
	v_mfma_f32_32x32x16_bf16 v[80:95], v[222:225], v[124:127], v[80:95]
	ds_read_b128 v[222:225], v0 offset:17472
	s_waitcnt lgkmcnt(9)
	v_mfma_f32_32x32x16_bf16 v[80:95], v[226:229], v[120:123], v[80:95]
	ds_read_b128 v[226:229], v0 offset:17504
	s_waitcnt lgkmcnt(9)
	v_mfma_f32_32x32x16_bf16 v[80:95], v[206:209], v[116:119], v[80:95]
	ds_read_b128 v[206:209], v0 offset:17536
	s_waitcnt lgkmcnt(9)
	v_mfma_f32_32x32x16_bf16 v[80:95], v[210:213], v[112:115], v[80:95]
	ds_read_b128 v[210:213], v0 offset:17568
	s_waitcnt lgkmcnt(6)
	s_waitcnt lgkmcnt(5)
	v_mfma_f32_32x32x16_bf16 v[96:111], v[214:217], v[140:143], v[96:111]
	ds_read_b128 v[214:217], v0 offset:17600
	s_waitcnt lgkmcnt(5)
	v_mfma_f32_32x32x16_bf16 v[96:111], v[218:221], v[136:139], v[96:111]
	ds_read_b128 v[218:221], v0 offset:17632
	s_waitcnt lgkmcnt(5)
	v_mfma_f32_32x32x16_bf16 v[96:111], v[222:225], v[132:135], v[96:111]
	s_waitcnt lgkmcnt(4)
	v_mfma_f32_32x32x16_bf16 v[96:111], v[226:229], v[128:131], v[96:111]
	v_mov_b32_e32 v15, v80
	v_mov_b32_e32 v178, v85
	v_mov_b32_e32 v180, v86
	v_mov_b32_e32 v181, v87
	v_mov_b32_e32 v179, v88
	v_mov_b32_e32 v182, v89
	v_mov_b32_e32 v183, v90
	v_mov_b32_e32 v184, v91
	v_mov_b32_e32 v185, v92
	v_mov_b32_e32 v186, v93
	v_mov_b32_e32 v187, v94
	v_mov_b32_e32 v189, v95
	s_waitcnt lgkmcnt(3)
	v_mfma_f32_32x32x16_bf16 v[96:111], v[206:209], v[124:127], v[96:111]
	s_waitcnt lgkmcnt(2)
	v_mfma_f32_32x32x16_bf16 v[96:111], v[210:213], v[120:123], v[96:111]
	s_waitcnt lgkmcnt(1)
	v_mfma_f32_32x32x16_bf16 v[96:111], v[214:217], v[116:119], v[96:111]
	s_waitcnt lgkmcnt(0)
	v_mfma_f32_32x32x16_bf16 v[96:111], v[218:221], v[112:115], v[96:111]
	v_mov_b32_e32 v174, v81
	v_mov_b32_e32 v175, v82
	v_mov_b32_e32 v176, v83
	v_mov_b32_e32 v177, v84
	s_nop 7
	v_mov_b32_e32 v188, v96
	v_mov_b32_e32 v191, v97
	v_mov_b32_e32 v192, v98
	v_mov_b32_e32 v193, v99
	v_mov_b32_e32 v194, v100
	v_mov_b32_e32 v195, v101
	v_mov_b32_e32 v198, v102
	v_mov_b32_e32 v199, v103
	v_mov_b32_e32 v196, v104
	v_mov_b32_e32 v197, v105
	v_mov_b32_e32 v200, v106
	v_mov_b32_e32 v201, v107
	v_mov_b32_e32 v202, v108
	v_mov_b32_e32 v203, v109
	v_mov_b32_e32 v204, v110
	v_mov_b32_e32 v205, v111
	s_cbranch_scc0 .LBB0_686
	v_add_u32_e32 v0, s78, v148
	v_cmp_le_i32_e32 vcc, v0, v163
	v_add_u32_e32 v175, 2, v0
	v_add_u32_e32 v176, 3, v0
	v_cndmask_b32_e32 v15, v239, v80, vcc
	v_cmp_lt_i32_e32 vcc, v0, v163
	v_add_u32_e32 v177, 4, v0
	v_add_u32_e32 v178, 5, v0
	v_cndmask_b32_e32 v174, v239, v81, vcc
	v_cmp_le_i32_e32 vcc, v175, v163
	v_add_u32_e32 v179, 6, v0
	v_add_u32_e32 v182, 17, v0
	v_cndmask_b32_e32 v175, v239, v82, vcc
	v_cmp_le_i32_e32 vcc, v176, v163
	v_add_u32_e32 v183, 18, v0
	v_add_u32_e32 v184, 19, v0
	v_cndmask_b32_e32 v176, v239, v83, vcc
	v_cmp_le_i32_e32 vcc, v177, v163
	v_add_u32_e32 v185, 20, v0
	v_add_u32_e32 v186, 21, v0
	v_cndmask_b32_e32 v177, v239, v84, vcc
	v_cmp_le_i32_e32 vcc, v178, v163
	v_add_u32_e32 v187, 22, v0
	v_add_u32_e32 v188, 23, v0
	v_cndmask_b32_e32 v178, v239, v85, vcc
	v_cmp_le_i32_e32 vcc, v179, v163
	v_add_u32_e32 v179, 7, v0
	v_add_u32_e32 v191, 33, v0
	v_cndmask_b32_e32 v180, v239, v86, vcc
	v_cmp_le_i32_e32 vcc, v179, v163
	v_add_u32_e32 v179, 16, v0
	v_add_u32_e32 v192, 34, v0
	v_cndmask_b32_e32 v181, v239, v87, vcc
	v_cmp_le_i32_e32 vcc, v179, v163
	v_max3_f32 v14, v15, s23, v174
	v_add_u32_e32 v193, 35, v0
	v_cndmask_b32_e32 v179, v239, v88, vcc
	v_cmp_le_i32_e32 vcc, v182, v163
	v_max3_f32 v14, v14, v175, v176
	v_add_u32_e32 v194, 36, v0
	v_cndmask_b32_e32 v182, v239, v89, vcc
	v_cmp_le_i32_e32 vcc, v183, v163
	v_max3_f32 v14, v14, v177, v178
	v_add_u32_e32 v195, 37, v0
	v_cndmask_b32_e32 v183, v239, v90, vcc
	v_cmp_le_i32_e32 vcc, v184, v163
	v_max3_f32 v14, v14, v180, v181
	v_add_u32_e32 v196, 38, v0
	v_cndmask_b32_e32 v184, v239, v91, vcc
	v_cmp_le_i32_e32 vcc, v185, v163
	v_max3_f32 v14, v14, v179, v182
	v_max3_f32 v14, v14, v183, v184
	v_cndmask_b32_e32 v185, v239, v92, vcc
	v_cmp_le_i32_e32 vcc, v186, v163
	v_add_u32_e32 v197, 49, v0
	v_add_u32_e32 v200, 50, v0
	v_cndmask_b32_e32 v186, v239, v93, vcc
	v_cmp_le_i32_e32 vcc, v187, v163
	v_max3_f32 v14, v14, v185, v186
	v_add_u32_e32 v201, 51, v0
	v_cndmask_b32_e32 v187, v239, v94, vcc
	v_cmp_le_i32_e32 vcc, v188, v163
	v_add_u32_e32 v188, 32, v0
	v_add_u32_e32 v202, 52, v0
	v_cndmask_b32_e32 v189, v239, v95, vcc
	v_cmp_le_i32_e32 vcc, v188, v163
	v_max3_f32 v14, v14, v187, v189
	v_add_u32_e32 v203, 53, v0
	v_cndmask_b32_e32 v188, v239, v96, vcc
	v_cmp_le_i32_e32 vcc, v191, v163
	v_add_u32_e32 v204, 54, v0
	s_mov_b64 s[56:57], 0
	v_cndmask_b32_e32 v191, v239, v97, vcc
	v_cmp_le_i32_e32 vcc, v192, v163
	v_max3_f32 v14, v14, v188, v191
	s_nop 0
	v_cndmask_b32_e32 v192, v239, v98, vcc
	v_cmp_le_i32_e32 vcc, v193, v163
	s_nop 1
	v_cndmask_b32_e32 v193, v239, v99, vcc
	v_cmp_le_i32_e32 vcc, v194, v163
	v_max3_f32 v14, v14, v192, v193
	s_nop 0
	v_cndmask_b32_e32 v194, v239, v100, vcc
	v_cmp_le_i32_e32 vcc, v195, v163
	s_nop 1
	v_cndmask_b32_e32 v195, v239, v101, vcc
	v_cmp_le_i32_e32 vcc, v196, v163
	v_add_u32_e32 v196, 39, v0
	v_max3_f32 v14, v14, v194, v195
	v_cndmask_b32_e32 v198, v239, v102, vcc
	v_cmp_le_i32_e32 vcc, v196, v163
	v_add_u32_e32 v196, 48, v0
	v_add_u32_e32 v0, 55, v0
	v_cndmask_b32_e32 v199, v239, v103, vcc
	v_cmp_le_i32_e32 vcc, v196, v163
	v_max3_f32 v14, v14, v198, v199
	s_nop 0
	v_cndmask_b32_e32 v196, v239, v104, vcc
	v_cmp_le_i32_e32 vcc, v197, v163
	s_nop 1
	v_cndmask_b32_e32 v197, v239, v105, vcc
	v_cmp_le_i32_e32 vcc, v200, v163
	v_max3_f32 v14, v14, v196, v197
	s_nop 0
	v_cndmask_b32_e32 v200, v239, v106, vcc
	v_cmp_le_i32_e32 vcc, v201, v163
	s_nop 1
	v_cndmask_b32_e32 v201, v239, v107, vcc
	v_cmp_le_i32_e32 vcc, v202, v163
	v_max3_f32 v14, v14, v200, v201
	s_nop 0
	v_cndmask_b32_e32 v202, v239, v108, vcc
	v_cmp_le_i32_e32 vcc, v203, v163
	s_nop 1
	v_cndmask_b32_e32 v203, v239, v109, vcc
	v_cmp_le_i32_e32 vcc, v204, v163
	v_max3_f32 v14, v14, v202, v203
	s_nop 0
	v_cndmask_b32_e32 v204, v239, v110, vcc
	v_cmp_le_i32_e32 vcc, v0, v163
	s_nop 1
	v_cndmask_b32_e32 v205, v239, v111, vcc
	v_max3_f32 v0, v14, v204, v205

.LBB0_699:
	s_cmp_gt_i32 s76, s77
	s_mov_b64 s[56:57], 0
	s_cbranch_scc1 .LBB0_710
	v_lshl_add_u32 v0, s76, 2, v165
	ds_read_b128 v[2:5], v0
	ds_read_b128 v[6:9], v0 offset:16
	s_bitcmp1_b32 s18, 0
	s_cselect_b32 s18, 0x4400, 0
	v_add_u32_e32 v15, s18, v164
	s_waitcnt lgkmcnt(1)
	v_mov_b32_e32 v83, v5
	s_waitcnt lgkmcnt(0)
	v_mov_b32_e32 v84, v6
	v_mov_b32_e32 v85, v7
	v_mov_b32_e32 v86, v8
	v_mov_b32_e32 v87, v9
	ds_read_b128 v[6:9], v15 offset:8704
	v_mov_b32_e32 v82, v4
	v_mov_b32_e32 v81, v3
	v_mov_b32_e32 v80, v2
	ds_read_b128 v[2:5], v0 offset:64
	ds_read_b128 v[10:13], v0 offset:80
	s_or_b32 s18, s76, 63
	s_cmp_lt_i32 s18, s75
	s_mov_b64 s[56:57], -1
	s_waitcnt lgkmcnt(1)
	v_mov_b32_e32 v88, v2
	s_waitcnt lgkmcnt(0)
	v_mov_b32_e32 v92, v10
	v_mov_b32_e32 v89, v3
	v_mov_b32_e32 v93, v11
	v_mov_b32_e32 v90, v4
	v_mov_b32_e32 v94, v12
	v_mov_b32_e32 v91, v5
	v_mov_b32_e32 v95, v13
	ds_read_b128 v[2:5], v15 offset:8736
	s_nop 0
	v_mfma_f32_32x32x16_bf16 v[80:95], v[6:9], v[140:143], v[80:95]
	s_waitcnt lgkmcnt(0)
	v_mfma_f32_32x32x16_bf16 v[80:95], v[2:5], v[136:139], v[80:95]
	ds_read_b128 v[2:5], v15 offset:8768
	s_waitcnt lgkmcnt(0)
	v_mfma_f32_32x32x16_bf16 v[80:95], v[2:5], v[132:135], v[80:95]
	ds_read_b128 v[2:5], v15 offset:8800
	s_waitcnt lgkmcnt(0)
	v_mfma_f32_32x32x16_bf16 v[80:95], v[2:5], v[128:131], v[80:95]
	ds_read_b128 v[2:5], v15 offset:8832
	s_waitcnt lgkmcnt(0)
	v_mfma_f32_32x32x16_bf16 v[80:95], v[2:5], v[124:127], v[80:95]
	ds_read_b128 v[2:5], v15 offset:8864
	ds_read_b128 v[6:9], v0 offset:128
	ds_read_b128 v[10:13], v15 offset:8896
	s_waitcnt lgkmcnt(1)
	v_mov_b32_e32 v99, v9
	v_mov_b32_e32 v98, v8
	v_mov_b32_e32 v97, v7
	v_mfma_f32_32x32x16_bf16 v[80:95], v[2:5], v[120:123], v[80:95]
	ds_read_b128 v[2:5], v0 offset:144
	ds_read_b128 v[104:107], v0 offset:192
	ds_read_b128 v[108:111], v0 offset:208
	ds_read_b128 v[144:147], v15 offset:8928
	ds_read_b128 v[152:155], v15 offset:17408
	v_mov_b32_e32 v96, v6
	s_waitcnt lgkmcnt(4)
	v_mov_b32_e32 v100, v2
	v_mov_b32_e32 v101, v3
	v_mov_b32_e32 v102, v4
	v_mov_b32_e32 v103, v5
	s_waitcnt lgkmcnt(3)
	v_mov_b32_e32 v104, v104
	s_waitcnt lgkmcnt(2)
	v_mov_b32_e32 v108, v108
	v_mov_b32_e32 v105, v105
	v_mov_b32_e32 v109, v109
	v_mov_b32_e32 v106, v106
	v_mov_b32_e32 v110, v110
	v_mov_b32_e32 v107, v107
	v_mov_b32_e32 v111, v111
	ds_read_b128 v[2:5], v15 offset:17440
	v_mfma_f32_32x32x16_bf16 v[80:95], v[10:13], v[116:119], v[80:95]
	s_waitcnt lgkmcnt(1)
	v_mfma_f32_32x32x16_bf16 v[96:111], v[152:155], v[140:143], v[96:111]
	s_waitcnt lgkmcnt(0)
	v_mfma_f32_32x32x16_bf16 v[96:111], v[2:5], v[136:139], v[96:111]
	ds_read_b128 v[2:5], v15 offset:17472
	s_waitcnt lgkmcnt(0)
	v_mfma_f32_32x32x16_bf16 v[96:111], v[2:5], v[132:135], v[96:111]
	ds_read_b128 v[2:5], v15 offset:17504
	s_waitcnt lgkmcnt(0)
	v_mfma_f32_32x32x16_bf16 v[96:111], v[2:5], v[128:131], v[96:111]
	ds_read_b128 v[2:5], v15 offset:17536
	ds_read_b128 v[6:9], v15 offset:17568
	s_waitcnt lgkmcnt(1)
	v_mfma_f32_32x32x16_bf16 v[96:111], v[2:5], v[124:127], v[96:111]
	ds_read_b128 v[124:127], v15 offset:17600
	ds_read_b128 v[128:131], v15 offset:17632
	s_waitcnt lgkmcnt(2)
	v_mfma_f32_32x32x16_bf16 v[96:111], v[6:9], v[120:123], v[96:111]
	s_waitcnt lgkmcnt(1)
	v_mfma_f32_32x32x16_bf16 v[96:111], v[124:127], v[116:119], v[96:111]
	v_mfma_f32_32x32x16_bf16 v[80:95], v[144:147], v[112:115], v[80:95]
	s_waitcnt lgkmcnt(0)
	v_mfma_f32_32x32x16_bf16 v[96:111], v[128:131], v[112:115], v[96:111]
	s_nop 9
	v_mov_b32_e32 v2, v80
	v_mov_b32_e32 v3, v81
	v_mov_b32_e32 v4, v82
	v_mov_b32_e32 v5, v83
	v_mov_b32_e32 v6, v84
	v_mov_b32_e32 v7, v85
	v_mov_b32_e32 v9, v86
	v_mov_b32_e32 v11, v87
	v_mov_b32_e32 v8, v88
	v_mov_b32_e32 v10, v89
	v_mov_b32_e32 v12, v90
	v_mov_b32_e32 v13, v91
	v_mov_b32_e32 v15, v92
	v_mov_b32_e32 v116, v93
	v_mov_b32_e32 v117, v94
	v_mov_b32_e32 v118, v95
	v_mov_b32_e32 v112, v96
	v_mov_b32_e32 v113, v97
	v_mov_b32_e32 v114, v98
	v_mov_b32_e32 v115, v99
	v_mov_b32_e32 v119, v100
	v_mov_b32_e32 v120, v101
	v_mov_b32_e32 v123, v102
	v_mov_b32_e32 v124, v103
	v_mov_b32_e32 v121, v104
	v_mov_b32_e32 v122, v105
	v_mov_b32_e32 v125, v106
	v_mov_b32_e32 v126, v107
	v_mov_b32_e32 v127, v108
	v_mov_b32_e32 v128, v109
	v_mov_b32_e32 v129, v110
	v_mov_b32_e32 v130, v111
	s_cbranch_scc1 .LBB0_702
	v_or_b32_e32 v0, s76, v148
	v_cmp_le_i32_e32 vcc, v0, v163
	v_or_b32_e32 v4, 2, v0
	v_or_b32_e32 v5, 3, v0
	v_cndmask_b32_e32 v2, v239, v80, vcc
	v_cmp_lt_i32_e32 vcc, v0, v163
	v_or_b32_e32 v7, 5, v0
	v_or_b32_e32 v9, 6, v0
	v_cndmask_b32_e32 v3, v239, v81, vcc
	v_cmp_le_i32_e32 vcc, v4, v163
	v_max3_f32 v6, v2, s23, v3
	v_or_b32_e32 v10, 7, v0
	v_cndmask_b32_e32 v4, v239, v82, vcc
	v_cmp_le_i32_e32 vcc, v5, v163
	v_or_b32_e32 v13, 19, v0
	v_or_b32_e32 v113, 21, v0
	v_cndmask_b32_e32 v5, v239, v83, vcc
	v_max3_f32 v8, v6, v4, v5
	v_or_b32_e32 v6, 4, v0
	v_cmp_le_i32_e32 vcc, v6, v163
	v_or_b32_e32 v115, 35, v0
	v_or_b32_e32 v120, 37, v0
	v_cndmask_b32_e32 v6, v239, v84, vcc
	v_cmp_le_i32_e32 vcc, v7, v163
	v_or_b32_e32 v122, 38, v0
	v_or_b32_e32 v126, 51, v0
	v_cndmask_b32_e32 v7, v239, v85, vcc
	v_cmp_le_i32_e32 vcc, v9, v163
	v_max3_f32 v8, v8, v6, v7
	v_or_b32_e32 v128, 53, v0
	v_cndmask_b32_e32 v9, v239, v86, vcc
	v_cmp_le_i32_e32 vcc, v10, v163
	v_or_b32_e32 v10, 17, v0
	s_mov_b64 s[56:57], 0
	v_cndmask_b32_e32 v11, v239, v87, vcc
	v_max3_f32 v12, v8, v9, v11
	v_or_b32_e32 v8, 16, v0
	v_cmp_le_i32_e32 vcc, v8, v163
	s_nop 1
	v_cndmask_b32_e32 v8, v239, v88, vcc
	v_cmp_le_i32_e32 vcc, v10, v163
	s_nop 1
	v_cndmask_b32_e32 v10, v239, v89, vcc
	v_max3_f32 v15, v12, v8, v10
	v_or_b32_e32 v12, 18, v0
	v_cmp_le_i32_e32 vcc, v12, v163
	s_nop 1
	v_cndmask_b32_e32 v12, v239, v90, vcc
	v_cmp_le_i32_e32 vcc, v13, v163
	s_nop 1
	v_cndmask_b32_e32 v13, v239, v91, vcc
	v_max3_f32 v112, v15, v12, v13
	v_or_b32_e32 v15, 20, v0
	v_cmp_le_i32_e32 vcc, v15, v163
	s_nop 1
	v_cndmask_b32_e32 v15, v239, v92, vcc
	v_cmp_le_i32_e32 vcc, v113, v163
	v_or_b32_e32 v113, 22, v0
	s_nop 0
	v_cndmask_b32_e32 v116, v239, v93, vcc
	v_cmp_le_i32_e32 vcc, v113, v163
	v_or_b32_e32 v113, 23, v0
	v_max3_f32 v112, v112, v15, v116
	v_cndmask_b32_e32 v117, v239, v94, vcc
	v_cmp_le_i32_e32 vcc, v113, v163
	v_or_b32_e32 v113, 33, v0
	s_nop 0
	v_cndmask_b32_e32 v118, v239, v95, vcc
	v_max3_f32 v114, v112, v117, v118
	v_or_b32_e32 v112, 32, v0
	v_cmp_le_i32_e32 vcc, v112, v163
	s_nop 1
	v_cndmask_b32_e32 v112, v239, v96, vcc
	v_cmp_le_i32_e32 vcc, v113, v163
	s_nop 1
	v_cndmask_b32_e32 v113, v239, v97, vcc
	v_max3_f32 v119, v114, v112, v113
	v_or_b32_e32 v114, 34, v0
	v_cmp_le_i32_e32 vcc, v114, v163
	s_nop 1
	v_cndmask_b32_e32 v114, v239, v98, vcc
	v_cmp_le_i32_e32 vcc, v115, v163
	s_nop 1
	v_cndmask_b32_e32 v115, v239, v99, vcc
	v_max3_f32 v121, v119, v114, v115
	v_or_b32_e32 v119, 36, v0
	v_cmp_le_i32_e32 vcc, v119, v163
	s_nop 1
	v_cndmask_b32_e32 v119, v239, v100, vcc
	v_cmp_le_i32_e32 vcc, v120, v163
	s_nop 1
	v_cndmask_b32_e32 v120, v239, v101, vcc
	v_cmp_le_i32_e32 vcc, v122, v163
	v_or_b32_e32 v122, 39, v0
	v_max3_f32 v121, v121, v119, v120
	v_cndmask_b32_e32 v123, v239, v102, vcc
	v_cmp_le_i32_e32 vcc, v122, v163
	v_or_b32_e32 v122, 49, v0
	s_nop 0
	v_cndmask_b32_e32 v124, v239, v103, vcc
	v_max3_f32 v125, v121, v123, v124
	v_or_b32_e32 v121, 48, v0
	v_cmp_le_i32_e32 vcc, v121, v163
	s_nop 1
	v_cndmask_b32_e32 v121, v239, v104, vcc
	v_cmp_le_i32_e32 vcc, v122, v163
	s_nop 1
	v_cndmask_b32_e32 v122, v239, v105, vcc
	v_max3_f32 v127, v125, v121, v122
	v_or_b32_e32 v125, 50, v0
	v_cmp_le_i32_e32 vcc, v125, v163
	s_nop 1
	v_cndmask_b32_e32 v125, v239, v106, vcc
	v_cmp_le_i32_e32 vcc, v126, v163
	s_nop 1
	v_cndmask_b32_e32 v126, v239, v107, vcc
	v_max3_f32 v129, v127, v125, v126
	v_or_b32_e32 v127, 52, v0
	v_cmp_le_i32_e32 vcc, v127, v163
	s_nop 1
	v_cndmask_b32_e32 v127, v239, v108, vcc
	v_cmp_le_i32_e32 vcc, v128, v163
	s_nop 1
	v_cndmask_b32_e32 v128, v239, v109, vcc
	v_max3_f32 v131, v129, v127, v128
	v_or_b32_e32 v129, 54, v0
	v_cmp_le_i32_e32 vcc, v129, v163
	v_or_b32_e32 v0, 55, v0
	s_nop 0
	v_cndmask_b32_e32 v129, v239, v110, vcc
	v_cmp_le_i32_e32 vcc, v0, v163
	s_nop 1
	v_cndmask_b32_e32 v130, v239, v111, vcc
	v_max3_f32 v0, v131, v129, v130

.LBB0_713:
	v_add_f32_e32 v6, v8, v5
	v_mul_f32_e32 v6, 0xbfb8aa3b, v6
	v_cmp_lt_i32_e32 vcc, 46, v0
	s_nop 1
	v_cndmask_b32_e32 v6, v239, v6, vcc
	ds_write_b32 v4, v6 offset:4
	s_or_b64 exec, exec, s[12:13]
	s_and_saveexec_b64 s[0:1], s[4:5]
	s_cbranch_execnz .LBB0_675

.LBB0_715:
	v_add_f32_e32 v3, v3, v5
	v_mul_f32_e32 v3, 0xbfb8aa3b, v3
	v_cmp_lt_i32_e32 vcc, 44, v0
	s_nop 1
	v_cndmask_b32_e32 v3, v239, v3, vcc
	ds_write_b32 v4, v3 offset:12
	s_or_b64 exec, exec, s[0:1]
	s_and_saveexec_b64 s[0:1], s[8:9]
	s_cbranch_execnz .LBB0_677
	s_branch .LBB0_678
